# hand-written hgrn_sample (coalesced dwordx4 state I/O, packed recurrence) with nt state loads, on top of the nt row/stream loads
# speedup vs baseline: 1.0113x; 1.0113x over previous
; __device__ __forceinline__ void hgrn_sample(Frame& F) {
;     ...
;     for (int u = blockIdx.x; u < 512; u += F.G) {
;         const int b = u >> 2, h = u & 3, row0 = TP + b * 8;
;         float S[32];
; #pragma unroll
;         for (int j = 0; j < 32; ++j) S[j] = F.state_hgrn[(((size_t)b * 4 + h) * 128 + qd * 32 + j) * 128 + dv];
; #pragma unroll
;         for (int i = 0; i < 2; ++i) { const int idx = tid + 512 * i, t = idx >> 7, cc = idx & 127; const size_t ro = (size_t)(row0 + t) * 512 + h * 128 + cc;
;             qs[idx] = bf2f(F.Q[ro]); fs[idx] = __expf((float)F.LOGF[ro]); ks[idx] = 1.f - fs[idx]; }
;         float v[8];
; #pragma unroll
;         for (int t = 0; t < 8; ++t) v[t] = bf2f(F.V[(size_t)(row0 + t) * 512 + h * 128 + dv]);
;         const float ogv = F.onorm_g[h * 128 + dv]; bf16 gsv[2];
; #pragma unroll
;         for (int i = 0; i < 2; ++i) gsv[i] = F.GS[(size_t)(row0 + ((tid + 512 * i) >> 7)) * 512 + h * 128 + dv];
;         __syncthreads();
.LBB0_629:
	s_cmp_lt_i32 s70, 4
	s_cselect_b64 s[2:3], -1, 0
	s_and_b64 s[40:41], s[2:3], s[0:1]
	s_andn2_b64 vcc, exec, s[40:41]
	s_cbranch_vccnz .LBB0_704
	v_readlane_b32 s0, v254, 44
	v_readlane_b32 s14, v254, 58
	v_readlane_b32 s15, v254, 59
	s_add_u32 s33, s14, 0x4c2a000
	s_addc_u32 s42, s15, 0
	s_bitcmp0_b32 s88, 3
	s_cselect_b64 s[92:93], -1, 0
	s_and_b64 vcc, exec, s[92:93]
	v_readlane_b32 s1, v254, 45
	v_readlane_b32 s2, v254, 46
	v_readlane_b32 s3, v254, 47
	v_readlane_b32 s4, v254, 48
	v_readlane_b32 s5, v254, 49
	v_readlane_b32 s6, v254, 50
	v_readlane_b32 s7, v254, 51
	v_readlane_b32 s8, v254, 52
	v_readlane_b32 s9, v254, 53
	v_readlane_b32 s10, v254, 54
	v_readlane_b32 s11, v254, 55
	v_readlane_b32 s12, v254, 56
	v_readlane_b32 s13, v254, 57
	s_cbranch_vccnz .LBB0_644
	s_cmpk_gt_i32 s88, 0x1ff
	s_cbranch_scc1 .LBB0_644
	v_readfirstlane_b32 s43, v0
	v_readlane_b32 s44, v254, 11
	v_readlane_b32 s45, v254, 12
	v_readlane_b32 s46, v254, 33
	v_readlane_b32 s47, v254, 34
	v_readlane_b32 s48, v254, 19
	v_readlane_b32 s49, v254, 20
	v_readlane_b32 s50, v254, 58
	v_readlane_b32 s51, v254, 59
	v_and_b32_e32 v130, 15, v202
	v_lshrrev_b32_e32 v131, 4, v202
	s_lshr_b32 s43, s43, 6
	s_sub_u32 s48, s48, 0x4000
	s_subb_u32 s49, s49, 0
	s_add_u32 s50, s50, 0x4c2a000
	s_addc_u32 s51, s51, 0
	s_lshl_b32 s54, s43, 2
	v_add_u32_e32 v137, s54, v131
	v_and_b32_e32 v148, 1, v137
	v_lshrrev_b32_e32 v150, 1, v137
	v_lshlrev_b32_e32 v135, 4, v130
	v_lshl_add_u32 v135, v148, 8, v135
	v_lshl_add_u32 v132, v150, 12, v135
	v_lshlrev_b32_e32 v134, 5, v150
	v_add_u32_e32 v136, 0x8000, v132
	v_lshlrev_b32_e32 v133, 2, v0
	s_lshl_b32 s54, s43, 9
	s_add_i32 s54, s54, 0x8000
	v_lshl_add_u32 v141, v202, 3, s54
	s_mov_b32 s55, s88
.Lhs_loop_a:
	s_cmp_ge_u32 s55, 0x200
	s_cbranch_scc1 .Lhs_done_a
	s_lshr_b32 s56, s55, 2
	s_and_b32 s57, s55, 3
	s_lshl_b32 s58, s56, 3
	s_add_i32 s58, s58, 0x4000
	s_lshl_b32 s59, s55, 16
	s_add_u32 s60, s44, s59
	s_addc_u32 s61, s45, 0
	s_add_u32 s62, s50, s59
	s_addc_u32 s63, s51, 0
	global_load_dwordx4 v[2:5], v132, s[60:61] nt
	global_load_dwordx4 v[6:9], v132, s[60:61] offset:512 nt
	global_load_dwordx4 v[10:13], v132, s[60:61] offset:1024 nt
	global_load_dwordx4 v[14:17], v132, s[60:61] offset:1536 nt
	global_load_dwordx4 v[18:21], v132, s[60:61] offset:2048 nt
	global_load_dwordx4 v[22:25], v132, s[60:61] offset:2560 nt
	global_load_dwordx4 v[26:29], v132, s[60:61] offset:3072 nt
	global_load_dwordx4 v[30:33], v132, s[60:61] offset:3584 nt
	s_lshl_b32 s74, s58, 10
	s_lshl_b32 s75, s57, 8
	s_add_i32 s74, s74, s75
	v_lshrrev_b32_e32 v137, 7, v0
	v_and_b32_e32 v148, 0x7f, v0
	v_lshlrev_b32_e32 v148, 1, v148
	v_lshl_add_u32 v148, v137, 10, v148
	v_add_u32_e32 v148, s74, v148
	s_add_u32 s76, s48, 0x8600000
	s_addc_u32 s77, s49, 0
	global_load_ushort v152, v148, s[76:77]
	s_add_u32 s76, s76, 0x1000
	s_addc_u32 s77, s77, 0
	global_load_ushort v153, v148, s[76:77]
	s_add_u32 s76, s48, 0x9700000
	s_addc_u32 s77, s49, 0
	global_load_ushort v154, v148, s[76:77]
	s_add_u32 s76, s76, 0x1000
	s_addc_u32 s77, s77, 0
	global_load_ushort v155, v148, s[76:77]
	s_add_u32 s76, s48, 0xca00000
	s_addc_u32 s77, s49, 0
	global_load_ushort v156, v148, s[76:77]
	s_add_u32 s76, s76, 0x1000
	s_addc_u32 s77, s77, 0
	global_load_ushort v157, v148, s[76:77]
	s_lshl_b32 s75, s57, 9
	s_add_u32 s76, s46, s75
	s_addc_u32 s77, s47, 0
	v_lshlrev_b32_e32 v150, 3, v202
	global_load_dwordx2 v[138:139], v150, s[76:77]
	s_lshl_b32 s75, s43, 10
	s_add_i32 s75, s75, s74
	s_add_u32 s76, s48, 0xdb00000
	s_addc_u32 s77, s49, 0
	s_add_u32 s76, s76, s75
	s_addc_u32 s77, s77, 0
	v_lshlrev_b32_e32 v142, 2, v202
	global_load_dword v140, v142, s[76:77]
	s_waitcnt vmcnt(2)
	v_lshlrev_b32_e32 v152, 16, v152
	v_cvt_f32_f16_e32 v154, v154
	v_mul_f32_e32 v154, 0x3fb8aa3b, v154
	v_exp_f32_e32 v154, v154
	v_lshlrev_b32_e32 v156, 16, v156
	ds_write_b32 v133, v152 offset:8192
	ds_write_b32 v133, v156 offset:12288
	v_sub_f32_e32 v148, 1.0, v154
	ds_write_b32 v133, v154 offset:0
	ds_write_b32 v133, v148 offset:4096
	v_lshlrev_b32_e32 v153, 16, v153
	v_cvt_f32_f16_e32 v155, v155
	v_mul_f32_e32 v155, 0x3fb8aa3b, v155
	v_exp_f32_e32 v155, v155
	v_lshlrev_b32_e32 v157, 16, v157
	ds_write_b32 v133, v153 offset:10240
	ds_write_b32 v133, v157 offset:14336
	v_sub_f32_e32 v149, 1.0, v155
	ds_write_b32 v133, v155 offset:2048
	ds_write_b32 v133, v149 offset:6144
	v_mov_b32_e32 v34, 0
	v_mov_b32_e32 v35, 0
	v_mov_b32_e32 v36, 0
	v_mov_b32_e32 v37, 0
	v_mov_b32_e32 v38, 0
	v_mov_b32_e32 v39, 0
	v_mov_b32_e32 v40, 0
	v_mov_b32_e32 v41, 0
	v_mov_b32_e32 v42, 0
	v_mov_b32_e32 v43, 0
	v_mov_b32_e32 v44, 0
	v_mov_b32_e32 v45, 0
	v_mov_b32_e32 v46, 0
	v_mov_b32_e32 v47, 0
	v_mov_b32_e32 v48, 0
	v_mov_b32_e32 v49, 0
	v_mov_b32_e32 v50, 0
	v_mov_b32_e32 v51, 0
	v_mov_b32_e32 v52, 0
	v_mov_b32_e32 v53, 0
	v_mov_b32_e32 v54, 0
	v_mov_b32_e32 v55, 0
	v_mov_b32_e32 v56, 0
	v_mov_b32_e32 v57, 0
	v_mov_b32_e32 v58, 0
	v_mov_b32_e32 v59, 0
	v_mov_b32_e32 v60, 0
	v_mov_b32_e32 v61, 0
	v_mov_b32_e32 v62, 0
	v_mov_b32_e32 v63, 0
	v_mov_b32_e32 v64, 0
	v_mov_b32_e32 v65, 0
	s_waitcnt lgkmcnt(0)
	s_barrier
; #define LAS __attribute__((address_space(3)))
; __device__ __forceinline__ void hgrn_sample(Frame& F) {
;     ...
; #pragma unroll
;         for (int t = 0; t < 8; ++t) { float op = 0.f;
; #pragma unroll
;             for (int j4 = 0; j4 < 8; ++j4) { const f32x4 f4 = *(const LAS f32x4*)(fs + t * 128 + qd * 32 + 4 * j4), k4 = *(const LAS f32x4*)(ks + t * 128 + qd * 32 + 4 * j4), q4 = *(const LAS f32x4*)(qs + t * 128 + qd * 32 + 4 * j4);
; #pragma unroll
;                 for (int e = 0; e < 4; ++e) { float s = f4[e] * S[4 * j4 + e] + k4[e] * v[t]; S[4 * j4 + e] = s; op += q4[e] * s; } }
;             part[(qd * 8 + t) * 128 + dv] = op; }
	ds_read_b128 v[66:69], v134 offset:0
	ds_read_b128 v[70:73], v134 offset:16
	ds_read_b128 v[74:77], v134 offset:4096
	ds_read_b128 v[78:81], v134 offset:4112
	ds_read_b128 v[82:85], v134 offset:8192
	ds_read_b128 v[86:89], v134 offset:8208
	ds_read_b128 v[90:93], v135 offset:12288
	s_waitcnt vmcnt(0)
	ds_read_b128 v[94:97], v134 offset:512
	ds_read_b128 v[98:101], v134 offset:528
	ds_read_b128 v[102:105], v134 offset:4608
	ds_read_b128 v[106:109], v134 offset:4624
	ds_read_b128 v[110:113], v134 offset:8704
	ds_read_b128 v[114:117], v134 offset:8720
	ds_read_b128 v[118:121], v135 offset:12800
	s_waitcnt lgkmcnt(7)
	v_pk_mul_f32 v[122:123], v[74:75], v[90:91] op_sel:[0,0] op_sel_hi:[0,1]
	v_pk_mul_f32 v[124:125], v[74:75], v[92:93] op_sel:[0,0] op_sel_hi:[0,1]
	v_pk_fma_f32 v[2:3], v[66:67], v[2:3], v[122:123] op_sel:[0,0,0] op_sel_hi:[0,1,1]
	v_pk_fma_f32 v[4:5], v[66:67], v[4:5], v[124:125] op_sel:[0,0,0] op_sel_hi:[0,1,1]
	v_pk_fma_f32 v[34:35], v[82:83], v[2:3], v[34:35] op_sel:[0,0,0] op_sel_hi:[0,1,1]
	v_pk_fma_f32 v[36:37], v[82:83], v[4:5], v[36:37] op_sel:[0,0,0] op_sel_hi:[0,1,1]
	v_pk_mul_f32 v[126:127], v[74:75], v[90:91] op_sel:[1,0] op_sel_hi:[1,1]
	v_pk_mul_f32 v[128:129], v[74:75], v[92:93] op_sel:[1,0] op_sel_hi:[1,1]
	v_pk_fma_f32 v[6:7], v[66:67], v[6:7], v[126:127] op_sel:[1,0,0] op_sel_hi:[1,1,1]
	v_pk_fma_f32 v[8:9], v[66:67], v[8:9], v[128:129] op_sel:[1,0,0] op_sel_hi:[1,1,1]
	v_pk_fma_f32 v[34:35], v[82:83], v[6:7], v[34:35] op_sel:[1,0,0] op_sel_hi:[1,1,1]
	v_pk_fma_f32 v[36:37], v[82:83], v[8:9], v[36:37] op_sel:[1,0,0] op_sel_hi:[1,1,1]
	v_pk_mul_f32 v[122:123], v[76:77], v[90:91] op_sel:[0,0] op_sel_hi:[0,1]
	v_pk_mul_f32 v[124:125], v[76:77], v[92:93] op_sel:[0,0] op_sel_hi:[0,1]
	v_pk_fma_f32 v[10:11], v[68:69], v[10:11], v[122:123] op_sel:[0,0,0] op_sel_hi:[0,1,1]
	v_pk_fma_f32 v[12:13], v[68:69], v[12:13], v[124:125] op_sel:[0,0,0] op_sel_hi:[0,1,1]
	v_pk_fma_f32 v[34:35], v[84:85], v[10:11], v[34:35] op_sel:[0,0,0] op_sel_hi:[0,1,1]
	v_pk_fma_f32 v[36:37], v[84:85], v[12:13], v[36:37] op_sel:[0,0,0] op_sel_hi:[0,1,1]
	v_pk_mul_f32 v[126:127], v[76:77], v[90:91] op_sel:[1,0] op_sel_hi:[1,1]
	v_pk_mul_f32 v[128:129], v[76:77], v[92:93] op_sel:[1,0] op_sel_hi:[1,1]
	v_pk_fma_f32 v[14:15], v[68:69], v[14:15], v[126:127] op_sel:[1,0,0] op_sel_hi:[1,1,1]
	v_pk_fma_f32 v[16:17], v[68:69], v[16:17], v[128:129] op_sel:[1,0,0] op_sel_hi:[1,1,1]
	v_pk_fma_f32 v[34:35], v[84:85], v[14:15], v[34:35] op_sel:[1,0,0] op_sel_hi:[1,1,1]
	v_pk_fma_f32 v[36:37], v[84:85], v[16:17], v[36:37] op_sel:[1,0,0] op_sel_hi:[1,1,1]
	v_pk_mul_f32 v[122:123], v[78:79], v[90:91] op_sel:[0,0] op_sel_hi:[0,1]
	v_pk_mul_f32 v[124:125], v[78:79], v[92:93] op_sel:[0,0] op_sel_hi:[0,1]
	v_pk_fma_f32 v[18:19], v[70:71], v[18:19], v[122:123] op_sel:[0,0,0] op_sel_hi:[0,1,1]
	v_pk_fma_f32 v[20:21], v[70:71], v[20:21], v[124:125] op_sel:[0,0,0] op_sel_hi:[0,1,1]
	v_pk_fma_f32 v[34:35], v[86:87], v[18:19], v[34:35] op_sel:[0,0,0] op_sel_hi:[0,1,1]
	v_pk_fma_f32 v[36:37], v[86:87], v[20:21], v[36:37] op_sel:[0,0,0] op_sel_hi:[0,1,1]
	v_pk_mul_f32 v[126:127], v[78:79], v[90:91] op_sel:[1,0] op_sel_hi:[1,1]
	v_pk_mul_f32 v[128:129], v[78:79], v[92:93] op_sel:[1,0] op_sel_hi:[1,1]
	v_pk_fma_f32 v[22:23], v[70:71], v[22:23], v[126:127] op_sel:[1,0,0] op_sel_hi:[1,1,1]
	v_pk_fma_f32 v[24:25], v[70:71], v[24:25], v[128:129] op_sel:[1,0,0] op_sel_hi:[1,1,1]
	v_pk_fma_f32 v[34:35], v[86:87], v[22:23], v[34:35] op_sel:[1,0,0] op_sel_hi:[1,1,1]
	v_pk_fma_f32 v[36:37], v[86:87], v[24:25], v[36:37] op_sel:[1,0,0] op_sel_hi:[1,1,1]
	v_pk_mul_f32 v[122:123], v[80:81], v[90:91] op_sel:[0,0] op_sel_hi:[0,1]
	v_pk_mul_f32 v[124:125], v[80:81], v[92:93] op_sel:[0,0] op_sel_hi:[0,1]
	v_pk_fma_f32 v[26:27], v[72:73], v[26:27], v[122:123] op_sel:[0,0,0] op_sel_hi:[0,1,1]
	v_pk_fma_f32 v[28:29], v[72:73], v[28:29], v[124:125] op_sel:[0,0,0] op_sel_hi:[0,1,1]
	v_pk_fma_f32 v[34:35], v[88:89], v[26:27], v[34:35] op_sel:[0,0,0] op_sel_hi:[0,1,1]
	v_pk_fma_f32 v[36:37], v[88:89], v[28:29], v[36:37] op_sel:[0,0,0] op_sel_hi:[0,1,1]
	v_pk_mul_f32 v[126:127], v[80:81], v[90:91] op_sel:[1,0] op_sel_hi:[1,1]
	v_pk_mul_f32 v[128:129], v[80:81], v[92:93] op_sel:[1,0] op_sel_hi:[1,1]
	v_pk_fma_f32 v[30:31], v[72:73], v[30:31], v[126:127] op_sel:[1,0,0] op_sel_hi:[1,1,1]
	v_pk_fma_f32 v[32:33], v[72:73], v[32:33], v[128:129] op_sel:[1,0,0] op_sel_hi:[1,1,1]
	v_pk_fma_f32 v[34:35], v[88:89], v[30:31], v[34:35] op_sel:[1,0,0] op_sel_hi:[1,1,1]
	v_pk_fma_f32 v[36:37], v[88:89], v[32:33], v[36:37] op_sel:[1,0,0] op_sel_hi:[1,1,1]
	ds_write_b128 v136, v[34:37] offset:0
	ds_read_b128 v[66:69], v134 offset:1024
	ds_read_b128 v[70:73], v134 offset:1040
	ds_read_b128 v[74:77], v134 offset:5120
	ds_read_b128 v[78:81], v134 offset:5136
	ds_read_b128 v[82:85], v134 offset:9216
	ds_read_b128 v[86:89], v134 offset:9232
	ds_read_b128 v[90:93], v135 offset:13312
	s_waitcnt lgkmcnt(7)
; #define LAS __attribute__((address_space(3)))
; __device__ __forceinline__ void hgrn_sample(Frame& F) {
;     ...
; #pragma unroll
;         for (int t = 0; t < 8; ++t) { float op = 0.f;
; #pragma unroll
;             for (int j4 = 0; j4 < 8; ++j4) { const f32x4 f4 = *(const LAS f32x4*)(fs + t * 128 + qd * 32 + 4 * j4), k4 = *(const LAS f32x4*)(ks + t * 128 + qd * 32 + 4 * j4), q4 = *(const LAS f32x4*)(qs + t * 128 + qd * 32 + 4 * j4);
; #pragma unroll
;                 for (int e = 0; e < 4; ++e) { float s = f4[e] * S[4 * j4 + e] + k4[e] * v[t]; S[4 * j4 + e] = s; op += q4[e] * s; } }
;             part[(qd * 8 + t) * 128 + dv] = op; }
	v_pk_mul_f32 v[122:123], v[102:103], v[118:119] op_sel:[0,0] op_sel_hi:[0,1]
	v_pk_mul_f32 v[124:125], v[102:103], v[120:121] op_sel:[0,0] op_sel_hi:[0,1]
	v_pk_fma_f32 v[2:3], v[94:95], v[2:3], v[122:123] op_sel:[0,0,0] op_sel_hi:[0,1,1]
	v_pk_fma_f32 v[4:5], v[94:95], v[4:5], v[124:125] op_sel:[0,0,0] op_sel_hi:[0,1,1]
	v_pk_fma_f32 v[38:39], v[110:111], v[2:3], v[38:39] op_sel:[0,0,0] op_sel_hi:[0,1,1]
	v_pk_fma_f32 v[40:41], v[110:111], v[4:5], v[40:41] op_sel:[0,0,0] op_sel_hi:[0,1,1]
	v_pk_mul_f32 v[126:127], v[102:103], v[118:119] op_sel:[1,0] op_sel_hi:[1,1]
	v_pk_mul_f32 v[128:129], v[102:103], v[120:121] op_sel:[1,0] op_sel_hi:[1,1]
	v_pk_fma_f32 v[6:7], v[94:95], v[6:7], v[126:127] op_sel:[1,0,0] op_sel_hi:[1,1,1]
	v_pk_fma_f32 v[8:9], v[94:95], v[8:9], v[128:129] op_sel:[1,0,0] op_sel_hi:[1,1,1]
	v_pk_fma_f32 v[38:39], v[110:111], v[6:7], v[38:39] op_sel:[1,0,0] op_sel_hi:[1,1,1]
	v_pk_fma_f32 v[40:41], v[110:111], v[8:9], v[40:41] op_sel:[1,0,0] op_sel_hi:[1,1,1]
	v_pk_mul_f32 v[122:123], v[104:105], v[118:119] op_sel:[0,0] op_sel_hi:[0,1]
	v_pk_mul_f32 v[124:125], v[104:105], v[120:121] op_sel:[0,0] op_sel_hi:[0,1]
	v_pk_fma_f32 v[10:11], v[96:97], v[10:11], v[122:123] op_sel:[0,0,0] op_sel_hi:[0,1,1]
	v_pk_fma_f32 v[12:13], v[96:97], v[12:13], v[124:125] op_sel:[0,0,0] op_sel_hi:[0,1,1]
	v_pk_fma_f32 v[38:39], v[112:113], v[10:11], v[38:39] op_sel:[0,0,0] op_sel_hi:[0,1,1]
	v_pk_fma_f32 v[40:41], v[112:113], v[12:13], v[40:41] op_sel:[0,0,0] op_sel_hi:[0,1,1]
	v_pk_mul_f32 v[126:127], v[104:105], v[118:119] op_sel:[1,0] op_sel_hi:[1,1]
	v_pk_mul_f32 v[128:129], v[104:105], v[120:121] op_sel:[1,0] op_sel_hi:[1,1]
	v_pk_fma_f32 v[14:15], v[96:97], v[14:15], v[126:127] op_sel:[1,0,0] op_sel_hi:[1,1,1]
	v_pk_fma_f32 v[16:17], v[96:97], v[16:17], v[128:129] op_sel:[1,0,0] op_sel_hi:[1,1,1]
	v_pk_fma_f32 v[38:39], v[112:113], v[14:15], v[38:39] op_sel:[1,0,0] op_sel_hi:[1,1,1]
	v_pk_fma_f32 v[40:41], v[112:113], v[16:17], v[40:41] op_sel:[1,0,0] op_sel_hi:[1,1,1]
	v_pk_mul_f32 v[122:123], v[106:107], v[118:119] op_sel:[0,0] op_sel_hi:[0,1]
	v_pk_mul_f32 v[124:125], v[106:107], v[120:121] op_sel:[0,0] op_sel_hi:[0,1]
	v_pk_fma_f32 v[18:19], v[98:99], v[18:19], v[122:123] op_sel:[0,0,0] op_sel_hi:[0,1,1]
	v_pk_fma_f32 v[20:21], v[98:99], v[20:21], v[124:125] op_sel:[0,0,0] op_sel_hi:[0,1,1]
	v_pk_fma_f32 v[38:39], v[114:115], v[18:19], v[38:39] op_sel:[0,0,0] op_sel_hi:[0,1,1]
	v_pk_fma_f32 v[40:41], v[114:115], v[20:21], v[40:41] op_sel:[0,0,0] op_sel_hi:[0,1,1]
	v_pk_mul_f32 v[126:127], v[106:107], v[118:119] op_sel:[1,0] op_sel_hi:[1,1]
	v_pk_mul_f32 v[128:129], v[106:107], v[120:121] op_sel:[1,0] op_sel_hi:[1,1]
	v_pk_fma_f32 v[22:23], v[98:99], v[22:23], v[126:127] op_sel:[1,0,0] op_sel_hi:[1,1,1]
	v_pk_fma_f32 v[24:25], v[98:99], v[24:25], v[128:129] op_sel:[1,0,0] op_sel_hi:[1,1,1]
	v_pk_fma_f32 v[38:39], v[114:115], v[22:23], v[38:39] op_sel:[1,0,0] op_sel_hi:[1,1,1]
	v_pk_fma_f32 v[40:41], v[114:115], v[24:25], v[40:41] op_sel:[1,0,0] op_sel_hi:[1,1,1]
	v_pk_mul_f32 v[122:123], v[108:109], v[118:119] op_sel:[0,0] op_sel_hi:[0,1]
	v_pk_mul_f32 v[124:125], v[108:109], v[120:121] op_sel:[0,0] op_sel_hi:[0,1]
	v_pk_fma_f32 v[26:27], v[100:101], v[26:27], v[122:123] op_sel:[0,0,0] op_sel_hi:[0,1,1]
	v_pk_fma_f32 v[28:29], v[100:101], v[28:29], v[124:125] op_sel:[0,0,0] op_sel_hi:[0,1,1]
	v_pk_fma_f32 v[38:39], v[116:117], v[26:27], v[38:39] op_sel:[0,0,0] op_sel_hi:[0,1,1]
	v_pk_fma_f32 v[40:41], v[116:117], v[28:29], v[40:41] op_sel:[0,0,0] op_sel_hi:[0,1,1]
	v_pk_mul_f32 v[126:127], v[108:109], v[118:119] op_sel:[1,0] op_sel_hi:[1,1]
	v_pk_mul_f32 v[128:129], v[108:109], v[120:121] op_sel:[1,0] op_sel_hi:[1,1]
	v_pk_fma_f32 v[30:31], v[100:101], v[30:31], v[126:127] op_sel:[1,0,0] op_sel_hi:[1,1,1]
	v_pk_fma_f32 v[32:33], v[100:101], v[32:33], v[128:129] op_sel:[1,0,0] op_sel_hi:[1,1,1]
	v_pk_fma_f32 v[38:39], v[116:117], v[30:31], v[38:39] op_sel:[1,0,0] op_sel_hi:[1,1,1]
	v_pk_fma_f32 v[40:41], v[116:117], v[32:33], v[40:41] op_sel:[1,0,0] op_sel_hi:[1,1,1]
	ds_write_b128 v136, v[38:41] offset:512
	ds_read_b128 v[94:97], v134 offset:1536
	ds_read_b128 v[98:101], v134 offset:1552
	ds_read_b128 v[102:105], v134 offset:5632
	ds_read_b128 v[106:109], v134 offset:5648
	ds_read_b128 v[110:113], v134 offset:9728
	ds_read_b128 v[114:117], v134 offset:9744
	ds_read_b128 v[118:121], v135 offset:13824
	s_waitcnt lgkmcnt(7)
; #define LAS __attribute__((address_space(3)))
; __device__ __forceinline__ void hgrn_sample(Frame& F) {
;     ...
; #pragma unroll
;         for (int t = 0; t < 8; ++t) { float op = 0.f;
; #pragma unroll
;             for (int j4 = 0; j4 < 8; ++j4) { const f32x4 f4 = *(const LAS f32x4*)(fs + t * 128 + qd * 32 + 4 * j4), k4 = *(const LAS f32x4*)(ks + t * 128 + qd * 32 + 4 * j4), q4 = *(const LAS f32x4*)(qs + t * 128 + qd * 32 + 4 * j4);
; #pragma unroll
;                 for (int e = 0; e < 4; ++e) { float s = f4[e] * S[4 * j4 + e] + k4[e] * v[t]; S[4 * j4 + e] = s; op += q4[e] * s; } }
;             part[(qd * 8 + t) * 128 + dv] = op; }
	v_pk_mul_f32 v[122:123], v[74:75], v[90:91] op_sel:[0,0] op_sel_hi:[0,1]
	v_pk_mul_f32 v[124:125], v[74:75], v[92:93] op_sel:[0,0] op_sel_hi:[0,1]
	v_pk_fma_f32 v[2:3], v[66:67], v[2:3], v[122:123] op_sel:[0,0,0] op_sel_hi:[0,1,1]
	v_pk_fma_f32 v[4:5], v[66:67], v[4:5], v[124:125] op_sel:[0,0,0] op_sel_hi:[0,1,1]
	v_pk_fma_f32 v[42:43], v[82:83], v[2:3], v[42:43] op_sel:[0,0,0] op_sel_hi:[0,1,1]
	v_pk_fma_f32 v[44:45], v[82:83], v[4:5], v[44:45] op_sel:[0,0,0] op_sel_hi:[0,1,1]
	v_pk_mul_f32 v[126:127], v[74:75], v[90:91] op_sel:[1,0] op_sel_hi:[1,1]
	v_pk_mul_f32 v[128:129], v[74:75], v[92:93] op_sel:[1,0] op_sel_hi:[1,1]
	v_pk_fma_f32 v[6:7], v[66:67], v[6:7], v[126:127] op_sel:[1,0,0] op_sel_hi:[1,1,1]
	v_pk_fma_f32 v[8:9], v[66:67], v[8:9], v[128:129] op_sel:[1,0,0] op_sel_hi:[1,1,1]
	v_pk_fma_f32 v[42:43], v[82:83], v[6:7], v[42:43] op_sel:[1,0,0] op_sel_hi:[1,1,1]
	v_pk_fma_f32 v[44:45], v[82:83], v[8:9], v[44:45] op_sel:[1,0,0] op_sel_hi:[1,1,1]
	v_pk_mul_f32 v[122:123], v[76:77], v[90:91] op_sel:[0,0] op_sel_hi:[0,1]
	v_pk_mul_f32 v[124:125], v[76:77], v[92:93] op_sel:[0,0] op_sel_hi:[0,1]
	v_pk_fma_f32 v[10:11], v[68:69], v[10:11], v[122:123] op_sel:[0,0,0] op_sel_hi:[0,1,1]
	v_pk_fma_f32 v[12:13], v[68:69], v[12:13], v[124:125] op_sel:[0,0,0] op_sel_hi:[0,1,1]
	v_pk_fma_f32 v[42:43], v[84:85], v[10:11], v[42:43] op_sel:[0,0,0] op_sel_hi:[0,1,1]
	v_pk_fma_f32 v[44:45], v[84:85], v[12:13], v[44:45] op_sel:[0,0,0] op_sel_hi:[0,1,1]
	v_pk_mul_f32 v[126:127], v[76:77], v[90:91] op_sel:[1,0] op_sel_hi:[1,1]
	v_pk_mul_f32 v[128:129], v[76:77], v[92:93] op_sel:[1,0] op_sel_hi:[1,1]
	v_pk_fma_f32 v[14:15], v[68:69], v[14:15], v[126:127] op_sel:[1,0,0] op_sel_hi:[1,1,1]
	v_pk_fma_f32 v[16:17], v[68:69], v[16:17], v[128:129] op_sel:[1,0,0] op_sel_hi:[1,1,1]
	v_pk_fma_f32 v[42:43], v[84:85], v[14:15], v[42:43] op_sel:[1,0,0] op_sel_hi:[1,1,1]
	v_pk_fma_f32 v[44:45], v[84:85], v[16:17], v[44:45] op_sel:[1,0,0] op_sel_hi:[1,1,1]
	v_pk_mul_f32 v[122:123], v[78:79], v[90:91] op_sel:[0,0] op_sel_hi:[0,1]
	v_pk_mul_f32 v[124:125], v[78:79], v[92:93] op_sel:[0,0] op_sel_hi:[0,1]
	v_pk_fma_f32 v[18:19], v[70:71], v[18:19], v[122:123] op_sel:[0,0,0] op_sel_hi:[0,1,1]
	v_pk_fma_f32 v[20:21], v[70:71], v[20:21], v[124:125] op_sel:[0,0,0] op_sel_hi:[0,1,1]
	v_pk_fma_f32 v[42:43], v[86:87], v[18:19], v[42:43] op_sel:[0,0,0] op_sel_hi:[0,1,1]
	v_pk_fma_f32 v[44:45], v[86:87], v[20:21], v[44:45] op_sel:[0,0,0] op_sel_hi:[0,1,1]
	v_pk_mul_f32 v[126:127], v[78:79], v[90:91] op_sel:[1,0] op_sel_hi:[1,1]
	v_pk_mul_f32 v[128:129], v[78:79], v[92:93] op_sel:[1,0] op_sel_hi:[1,1]
	v_pk_fma_f32 v[22:23], v[70:71], v[22:23], v[126:127] op_sel:[1,0,0] op_sel_hi:[1,1,1]
	v_pk_fma_f32 v[24:25], v[70:71], v[24:25], v[128:129] op_sel:[1,0,0] op_sel_hi:[1,1,1]
	v_pk_fma_f32 v[42:43], v[86:87], v[22:23], v[42:43] op_sel:[1,0,0] op_sel_hi:[1,1,1]
	v_pk_fma_f32 v[44:45], v[86:87], v[24:25], v[44:45] op_sel:[1,0,0] op_sel_hi:[1,1,1]
	v_pk_mul_f32 v[122:123], v[80:81], v[90:91] op_sel:[0,0] op_sel_hi:[0,1]
	v_pk_mul_f32 v[124:125], v[80:81], v[92:93] op_sel:[0,0] op_sel_hi:[0,1]
	v_pk_fma_f32 v[26:27], v[72:73], v[26:27], v[122:123] op_sel:[0,0,0] op_sel_hi:[0,1,1]
	v_pk_fma_f32 v[28:29], v[72:73], v[28:29], v[124:125] op_sel:[0,0,0] op_sel_hi:[0,1,1]
	v_pk_fma_f32 v[42:43], v[88:89], v[26:27], v[42:43] op_sel:[0,0,0] op_sel_hi:[0,1,1]
	v_pk_fma_f32 v[44:45], v[88:89], v[28:29], v[44:45] op_sel:[0,0,0] op_sel_hi:[0,1,1]
	v_pk_mul_f32 v[126:127], v[80:81], v[90:91] op_sel:[1,0] op_sel_hi:[1,1]
	v_pk_mul_f32 v[128:129], v[80:81], v[92:93] op_sel:[1,0] op_sel_hi:[1,1]
	v_pk_fma_f32 v[30:31], v[72:73], v[30:31], v[126:127] op_sel:[1,0,0] op_sel_hi:[1,1,1]
	v_pk_fma_f32 v[32:33], v[72:73], v[32:33], v[128:129] op_sel:[1,0,0] op_sel_hi:[1,1,1]
	v_pk_fma_f32 v[42:43], v[88:89], v[30:31], v[42:43] op_sel:[1,0,0] op_sel_hi:[1,1,1]
	v_pk_fma_f32 v[44:45], v[88:89], v[32:33], v[44:45] op_sel:[1,0,0] op_sel_hi:[1,1,1]
	ds_write_b128 v136, v[42:45] offset:1024
	ds_read_b128 v[66:69], v134 offset:2048
	ds_read_b128 v[70:73], v134 offset:2064
	ds_read_b128 v[74:77], v134 offset:6144
	ds_read_b128 v[78:81], v134 offset:6160
	ds_read_b128 v[82:85], v134 offset:10240
	ds_read_b128 v[86:89], v134 offset:10256
	ds_read_b128 v[90:93], v135 offset:14336
	s_waitcnt lgkmcnt(7)
; #define LAS __attribute__((address_space(3)))
; __device__ __forceinline__ void hgrn_sample(Frame& F) {
;     ...
; #pragma unroll
;         for (int t = 0; t < 8; ++t) { float op = 0.f;
; #pragma unroll
;             for (int j4 = 0; j4 < 8; ++j4) { const f32x4 f4 = *(const LAS f32x4*)(fs + t * 128 + qd * 32 + 4 * j4), k4 = *(const LAS f32x4*)(ks + t * 128 + qd * 32 + 4 * j4), q4 = *(const LAS f32x4*)(qs + t * 128 + qd * 32 + 4 * j4);
; #pragma unroll
;                 for (int e = 0; e < 4; ++e) { float s = f4[e] * S[4 * j4 + e] + k4[e] * v[t]; S[4 * j4 + e] = s; op += q4[e] * s; } }
;             part[(qd * 8 + t) * 128 + dv] = op; }
	v_pk_mul_f32 v[122:123], v[102:103], v[118:119] op_sel:[0,0] op_sel_hi:[0,1]
	v_pk_mul_f32 v[124:125], v[102:103], v[120:121] op_sel:[0,0] op_sel_hi:[0,1]
	v_pk_fma_f32 v[2:3], v[94:95], v[2:3], v[122:123] op_sel:[0,0,0] op_sel_hi:[0,1,1]
	v_pk_fma_f32 v[4:5], v[94:95], v[4:5], v[124:125] op_sel:[0,0,0] op_sel_hi:[0,1,1]
	v_pk_fma_f32 v[46:47], v[110:111], v[2:3], v[46:47] op_sel:[0,0,0] op_sel_hi:[0,1,1]
	v_pk_fma_f32 v[48:49], v[110:111], v[4:5], v[48:49] op_sel:[0,0,0] op_sel_hi:[0,1,1]
	v_pk_mul_f32 v[126:127], v[102:103], v[118:119] op_sel:[1,0] op_sel_hi:[1,1]
	v_pk_mul_f32 v[128:129], v[102:103], v[120:121] op_sel:[1,0] op_sel_hi:[1,1]
	v_pk_fma_f32 v[6:7], v[94:95], v[6:7], v[126:127] op_sel:[1,0,0] op_sel_hi:[1,1,1]
	v_pk_fma_f32 v[8:9], v[94:95], v[8:9], v[128:129] op_sel:[1,0,0] op_sel_hi:[1,1,1]
	v_pk_fma_f32 v[46:47], v[110:111], v[6:7], v[46:47] op_sel:[1,0,0] op_sel_hi:[1,1,1]
	v_pk_fma_f32 v[48:49], v[110:111], v[8:9], v[48:49] op_sel:[1,0,0] op_sel_hi:[1,1,1]
	v_pk_mul_f32 v[122:123], v[104:105], v[118:119] op_sel:[0,0] op_sel_hi:[0,1]
	v_pk_mul_f32 v[124:125], v[104:105], v[120:121] op_sel:[0,0] op_sel_hi:[0,1]
	v_pk_fma_f32 v[10:11], v[96:97], v[10:11], v[122:123] op_sel:[0,0,0] op_sel_hi:[0,1,1]
	v_pk_fma_f32 v[12:13], v[96:97], v[12:13], v[124:125] op_sel:[0,0,0] op_sel_hi:[0,1,1]
	v_pk_fma_f32 v[46:47], v[112:113], v[10:11], v[46:47] op_sel:[0,0,0] op_sel_hi:[0,1,1]
	v_pk_fma_f32 v[48:49], v[112:113], v[12:13], v[48:49] op_sel:[0,0,0] op_sel_hi:[0,1,1]
	v_pk_mul_f32 v[126:127], v[104:105], v[118:119] op_sel:[1,0] op_sel_hi:[1,1]
	v_pk_mul_f32 v[128:129], v[104:105], v[120:121] op_sel:[1,0] op_sel_hi:[1,1]
	v_pk_fma_f32 v[14:15], v[96:97], v[14:15], v[126:127] op_sel:[1,0,0] op_sel_hi:[1,1,1]
	v_pk_fma_f32 v[16:17], v[96:97], v[16:17], v[128:129] op_sel:[1,0,0] op_sel_hi:[1,1,1]
	v_pk_fma_f32 v[46:47], v[112:113], v[14:15], v[46:47] op_sel:[1,0,0] op_sel_hi:[1,1,1]
	v_pk_fma_f32 v[48:49], v[112:113], v[16:17], v[48:49] op_sel:[1,0,0] op_sel_hi:[1,1,1]
	v_pk_mul_f32 v[122:123], v[106:107], v[118:119] op_sel:[0,0] op_sel_hi:[0,1]
	v_pk_mul_f32 v[124:125], v[106:107], v[120:121] op_sel:[0,0] op_sel_hi:[0,1]
	v_pk_fma_f32 v[18:19], v[98:99], v[18:19], v[122:123] op_sel:[0,0,0] op_sel_hi:[0,1,1]
	v_pk_fma_f32 v[20:21], v[98:99], v[20:21], v[124:125] op_sel:[0,0,0] op_sel_hi:[0,1,1]
	v_pk_fma_f32 v[46:47], v[114:115], v[18:19], v[46:47] op_sel:[0,0,0] op_sel_hi:[0,1,1]
	v_pk_fma_f32 v[48:49], v[114:115], v[20:21], v[48:49] op_sel:[0,0,0] op_sel_hi:[0,1,1]
	v_pk_mul_f32 v[126:127], v[106:107], v[118:119] op_sel:[1,0] op_sel_hi:[1,1]
	v_pk_mul_f32 v[128:129], v[106:107], v[120:121] op_sel:[1,0] op_sel_hi:[1,1]
	v_pk_fma_f32 v[22:23], v[98:99], v[22:23], v[126:127] op_sel:[1,0,0] op_sel_hi:[1,1,1]
	v_pk_fma_f32 v[24:25], v[98:99], v[24:25], v[128:129] op_sel:[1,0,0] op_sel_hi:[1,1,1]
	v_pk_fma_f32 v[46:47], v[114:115], v[22:23], v[46:47] op_sel:[1,0,0] op_sel_hi:[1,1,1]
	v_pk_fma_f32 v[48:49], v[114:115], v[24:25], v[48:49] op_sel:[1,0,0] op_sel_hi:[1,1,1]
	v_pk_mul_f32 v[122:123], v[108:109], v[118:119] op_sel:[0,0] op_sel_hi:[0,1]
	v_pk_mul_f32 v[124:125], v[108:109], v[120:121] op_sel:[0,0] op_sel_hi:[0,1]
	v_pk_fma_f32 v[26:27], v[100:101], v[26:27], v[122:123] op_sel:[0,0,0] op_sel_hi:[0,1,1]
	v_pk_fma_f32 v[28:29], v[100:101], v[28:29], v[124:125] op_sel:[0,0,0] op_sel_hi:[0,1,1]
	v_pk_fma_f32 v[46:47], v[116:117], v[26:27], v[46:47] op_sel:[0,0,0] op_sel_hi:[0,1,1]
	v_pk_fma_f32 v[48:49], v[116:117], v[28:29], v[48:49] op_sel:[0,0,0] op_sel_hi:[0,1,1]
	v_pk_mul_f32 v[126:127], v[108:109], v[118:119] op_sel:[1,0] op_sel_hi:[1,1]
	v_pk_mul_f32 v[128:129], v[108:109], v[120:121] op_sel:[1,0] op_sel_hi:[1,1]
	v_pk_fma_f32 v[30:31], v[100:101], v[30:31], v[126:127] op_sel:[1,0,0] op_sel_hi:[1,1,1]
	v_pk_fma_f32 v[32:33], v[100:101], v[32:33], v[128:129] op_sel:[1,0,0] op_sel_hi:[1,1,1]
	v_pk_fma_f32 v[46:47], v[116:117], v[30:31], v[46:47] op_sel:[1,0,0] op_sel_hi:[1,1,1]
	v_pk_fma_f32 v[48:49], v[116:117], v[32:33], v[48:49] op_sel:[1,0,0] op_sel_hi:[1,1,1]
	ds_write_b128 v136, v[46:49] offset:1536
	ds_read_b128 v[94:97], v134 offset:2560
	ds_read_b128 v[98:101], v134 offset:2576
	ds_read_b128 v[102:105], v134 offset:6656
	ds_read_b128 v[106:109], v134 offset:6672
	ds_read_b128 v[110:113], v134 offset:10752
	ds_read_b128 v[114:117], v134 offset:10768
	ds_read_b128 v[118:121], v135 offset:14848
	s_waitcnt lgkmcnt(7)
; #define LAS __attribute__((address_space(3)))
; __device__ __forceinline__ void hgrn_sample(Frame& F) {
;     ...
; #pragma unroll
;         for (int t = 0; t < 8; ++t) { float op = 0.f;
; #pragma unroll
;             for (int j4 = 0; j4 < 8; ++j4) { const f32x4 f4 = *(const LAS f32x4*)(fs + t * 128 + qd * 32 + 4 * j4), k4 = *(const LAS f32x4*)(ks + t * 128 + qd * 32 + 4 * j4), q4 = *(const LAS f32x4*)(qs + t * 128 + qd * 32 + 4 * j4);
; #pragma unroll
;                 for (int e = 0; e < 4; ++e) { float s = f4[e] * S[4 * j4 + e] + k4[e] * v[t]; S[4 * j4 + e] = s; op += q4[e] * s; } }
;             part[(qd * 8 + t) * 128 + dv] = op; }
	v_pk_mul_f32 v[122:123], v[74:75], v[90:91] op_sel:[0,0] op_sel_hi:[0,1]
	v_pk_mul_f32 v[124:125], v[74:75], v[92:93] op_sel:[0,0] op_sel_hi:[0,1]
	v_pk_fma_f32 v[2:3], v[66:67], v[2:3], v[122:123] op_sel:[0,0,0] op_sel_hi:[0,1,1]
	v_pk_fma_f32 v[4:5], v[66:67], v[4:5], v[124:125] op_sel:[0,0,0] op_sel_hi:[0,1,1]
	v_pk_fma_f32 v[50:51], v[82:83], v[2:3], v[50:51] op_sel:[0,0,0] op_sel_hi:[0,1,1]
	v_pk_fma_f32 v[52:53], v[82:83], v[4:5], v[52:53] op_sel:[0,0,0] op_sel_hi:[0,1,1]
	v_pk_mul_f32 v[126:127], v[74:75], v[90:91] op_sel:[1,0] op_sel_hi:[1,1]
	v_pk_mul_f32 v[128:129], v[74:75], v[92:93] op_sel:[1,0] op_sel_hi:[1,1]
	v_pk_fma_f32 v[6:7], v[66:67], v[6:7], v[126:127] op_sel:[1,0,0] op_sel_hi:[1,1,1]
	v_pk_fma_f32 v[8:9], v[66:67], v[8:9], v[128:129] op_sel:[1,0,0] op_sel_hi:[1,1,1]
	v_pk_fma_f32 v[50:51], v[82:83], v[6:7], v[50:51] op_sel:[1,0,0] op_sel_hi:[1,1,1]
	v_pk_fma_f32 v[52:53], v[82:83], v[8:9], v[52:53] op_sel:[1,0,0] op_sel_hi:[1,1,1]
	v_pk_mul_f32 v[122:123], v[76:77], v[90:91] op_sel:[0,0] op_sel_hi:[0,1]
	v_pk_mul_f32 v[124:125], v[76:77], v[92:93] op_sel:[0,0] op_sel_hi:[0,1]
	v_pk_fma_f32 v[10:11], v[68:69], v[10:11], v[122:123] op_sel:[0,0,0] op_sel_hi:[0,1,1]
	v_pk_fma_f32 v[12:13], v[68:69], v[12:13], v[124:125] op_sel:[0,0,0] op_sel_hi:[0,1,1]
	v_pk_fma_f32 v[50:51], v[84:85], v[10:11], v[50:51] op_sel:[0,0,0] op_sel_hi:[0,1,1]
	v_pk_fma_f32 v[52:53], v[84:85], v[12:13], v[52:53] op_sel:[0,0,0] op_sel_hi:[0,1,1]
	v_pk_mul_f32 v[126:127], v[76:77], v[90:91] op_sel:[1,0] op_sel_hi:[1,1]
	v_pk_mul_f32 v[128:129], v[76:77], v[92:93] op_sel:[1,0] op_sel_hi:[1,1]
	v_pk_fma_f32 v[14:15], v[68:69], v[14:15], v[126:127] op_sel:[1,0,0] op_sel_hi:[1,1,1]
	v_pk_fma_f32 v[16:17], v[68:69], v[16:17], v[128:129] op_sel:[1,0,0] op_sel_hi:[1,1,1]
	v_pk_fma_f32 v[50:51], v[84:85], v[14:15], v[50:51] op_sel:[1,0,0] op_sel_hi:[1,1,1]
	v_pk_fma_f32 v[52:53], v[84:85], v[16:17], v[52:53] op_sel:[1,0,0] op_sel_hi:[1,1,1]
	v_pk_mul_f32 v[122:123], v[78:79], v[90:91] op_sel:[0,0] op_sel_hi:[0,1]
	v_pk_mul_f32 v[124:125], v[78:79], v[92:93] op_sel:[0,0] op_sel_hi:[0,1]
	v_pk_fma_f32 v[18:19], v[70:71], v[18:19], v[122:123] op_sel:[0,0,0] op_sel_hi:[0,1,1]
	v_pk_fma_f32 v[20:21], v[70:71], v[20:21], v[124:125] op_sel:[0,0,0] op_sel_hi:[0,1,1]
	v_pk_fma_f32 v[50:51], v[86:87], v[18:19], v[50:51] op_sel:[0,0,0] op_sel_hi:[0,1,1]
	v_pk_fma_f32 v[52:53], v[86:87], v[20:21], v[52:53] op_sel:[0,0,0] op_sel_hi:[0,1,1]
	v_pk_mul_f32 v[126:127], v[78:79], v[90:91] op_sel:[1,0] op_sel_hi:[1,1]
	v_pk_mul_f32 v[128:129], v[78:79], v[92:93] op_sel:[1,0] op_sel_hi:[1,1]
	v_pk_fma_f32 v[22:23], v[70:71], v[22:23], v[126:127] op_sel:[1,0,0] op_sel_hi:[1,1,1]
	v_pk_fma_f32 v[24:25], v[70:71], v[24:25], v[128:129] op_sel:[1,0,0] op_sel_hi:[1,1,1]
	v_pk_fma_f32 v[50:51], v[86:87], v[22:23], v[50:51] op_sel:[1,0,0] op_sel_hi:[1,1,1]
	v_pk_fma_f32 v[52:53], v[86:87], v[24:25], v[52:53] op_sel:[1,0,0] op_sel_hi:[1,1,1]
	v_pk_mul_f32 v[122:123], v[80:81], v[90:91] op_sel:[0,0] op_sel_hi:[0,1]
	v_pk_mul_f32 v[124:125], v[80:81], v[92:93] op_sel:[0,0] op_sel_hi:[0,1]
	v_pk_fma_f32 v[26:27], v[72:73], v[26:27], v[122:123] op_sel:[0,0,0] op_sel_hi:[0,1,1]
	v_pk_fma_f32 v[28:29], v[72:73], v[28:29], v[124:125] op_sel:[0,0,0] op_sel_hi:[0,1,1]
	v_pk_fma_f32 v[50:51], v[88:89], v[26:27], v[50:51] op_sel:[0,0,0] op_sel_hi:[0,1,1]
	v_pk_fma_f32 v[52:53], v[88:89], v[28:29], v[52:53] op_sel:[0,0,0] op_sel_hi:[0,1,1]
	v_pk_mul_f32 v[126:127], v[80:81], v[90:91] op_sel:[1,0] op_sel_hi:[1,1]
	v_pk_mul_f32 v[128:129], v[80:81], v[92:93] op_sel:[1,0] op_sel_hi:[1,1]
	v_pk_fma_f32 v[30:31], v[72:73], v[30:31], v[126:127] op_sel:[1,0,0] op_sel_hi:[1,1,1]
	v_pk_fma_f32 v[32:33], v[72:73], v[32:33], v[128:129] op_sel:[1,0,0] op_sel_hi:[1,1,1]
	v_pk_fma_f32 v[50:51], v[88:89], v[30:31], v[50:51] op_sel:[1,0,0] op_sel_hi:[1,1,1]
	v_pk_fma_f32 v[52:53], v[88:89], v[32:33], v[52:53] op_sel:[1,0,0] op_sel_hi:[1,1,1]
	ds_write_b128 v136, v[50:53] offset:2048
	ds_read_b128 v[66:69], v134 offset:3072
	ds_read_b128 v[70:73], v134 offset:3088
	ds_read_b128 v[74:77], v134 offset:7168
	ds_read_b128 v[78:81], v134 offset:7184
	ds_read_b128 v[82:85], v134 offset:11264
	ds_read_b128 v[86:89], v134 offset:11280
	ds_read_b128 v[90:93], v135 offset:15360
	s_waitcnt lgkmcnt(7)
; #define LAS __attribute__((address_space(3)))
; __device__ __forceinline__ void hgrn_sample(Frame& F) {
;     ...
; #pragma unroll
;         for (int t = 0; t < 8; ++t) { float op = 0.f;
; #pragma unroll
;             for (int j4 = 0; j4 < 8; ++j4) { const f32x4 f4 = *(const LAS f32x4*)(fs + t * 128 + qd * 32 + 4 * j4), k4 = *(const LAS f32x4*)(ks + t * 128 + qd * 32 + 4 * j4), q4 = *(const LAS f32x4*)(qs + t * 128 + qd * 32 + 4 * j4);
; #pragma unroll
;                 for (int e = 0; e < 4; ++e) { float s = f4[e] * S[4 * j4 + e] + k4[e] * v[t]; S[4 * j4 + e] = s; op += q4[e] * s; } }
;             part[(qd * 8 + t) * 128 + dv] = op; }
	v_pk_mul_f32 v[122:123], v[102:103], v[118:119] op_sel:[0,0] op_sel_hi:[0,1]
	v_pk_mul_f32 v[124:125], v[102:103], v[120:121] op_sel:[0,0] op_sel_hi:[0,1]
	v_pk_fma_f32 v[2:3], v[94:95], v[2:3], v[122:123] op_sel:[0,0,0] op_sel_hi:[0,1,1]
	v_pk_fma_f32 v[4:5], v[94:95], v[4:5], v[124:125] op_sel:[0,0,0] op_sel_hi:[0,1,1]
	v_pk_fma_f32 v[54:55], v[110:111], v[2:3], v[54:55] op_sel:[0,0,0] op_sel_hi:[0,1,1]
	v_pk_fma_f32 v[56:57], v[110:111], v[4:5], v[56:57] op_sel:[0,0,0] op_sel_hi:[0,1,1]
	v_pk_mul_f32 v[126:127], v[102:103], v[118:119] op_sel:[1,0] op_sel_hi:[1,1]
	v_pk_mul_f32 v[128:129], v[102:103], v[120:121] op_sel:[1,0] op_sel_hi:[1,1]
	v_pk_fma_f32 v[6:7], v[94:95], v[6:7], v[126:127] op_sel:[1,0,0] op_sel_hi:[1,1,1]
	v_pk_fma_f32 v[8:9], v[94:95], v[8:9], v[128:129] op_sel:[1,0,0] op_sel_hi:[1,1,1]
	v_pk_fma_f32 v[54:55], v[110:111], v[6:7], v[54:55] op_sel:[1,0,0] op_sel_hi:[1,1,1]
	v_pk_fma_f32 v[56:57], v[110:111], v[8:9], v[56:57] op_sel:[1,0,0] op_sel_hi:[1,1,1]
	v_pk_mul_f32 v[122:123], v[104:105], v[118:119] op_sel:[0,0] op_sel_hi:[0,1]
	v_pk_mul_f32 v[124:125], v[104:105], v[120:121] op_sel:[0,0] op_sel_hi:[0,1]
	v_pk_fma_f32 v[10:11], v[96:97], v[10:11], v[122:123] op_sel:[0,0,0] op_sel_hi:[0,1,1]
	v_pk_fma_f32 v[12:13], v[96:97], v[12:13], v[124:125] op_sel:[0,0,0] op_sel_hi:[0,1,1]
	v_pk_fma_f32 v[54:55], v[112:113], v[10:11], v[54:55] op_sel:[0,0,0] op_sel_hi:[0,1,1]
	v_pk_fma_f32 v[56:57], v[112:113], v[12:13], v[56:57] op_sel:[0,0,0] op_sel_hi:[0,1,1]
	v_pk_mul_f32 v[126:127], v[104:105], v[118:119] op_sel:[1,0] op_sel_hi:[1,1]
	v_pk_mul_f32 v[128:129], v[104:105], v[120:121] op_sel:[1,0] op_sel_hi:[1,1]
	v_pk_fma_f32 v[14:15], v[96:97], v[14:15], v[126:127] op_sel:[1,0,0] op_sel_hi:[1,1,1]
	v_pk_fma_f32 v[16:17], v[96:97], v[16:17], v[128:129] op_sel:[1,0,0] op_sel_hi:[1,1,1]
	v_pk_fma_f32 v[54:55], v[112:113], v[14:15], v[54:55] op_sel:[1,0,0] op_sel_hi:[1,1,1]
	v_pk_fma_f32 v[56:57], v[112:113], v[16:17], v[56:57] op_sel:[1,0,0] op_sel_hi:[1,1,1]
	v_pk_mul_f32 v[122:123], v[106:107], v[118:119] op_sel:[0,0] op_sel_hi:[0,1]
	v_pk_mul_f32 v[124:125], v[106:107], v[120:121] op_sel:[0,0] op_sel_hi:[0,1]
	v_pk_fma_f32 v[18:19], v[98:99], v[18:19], v[122:123] op_sel:[0,0,0] op_sel_hi:[0,1,1]
	v_pk_fma_f32 v[20:21], v[98:99], v[20:21], v[124:125] op_sel:[0,0,0] op_sel_hi:[0,1,1]
	v_pk_fma_f32 v[54:55], v[114:115], v[18:19], v[54:55] op_sel:[0,0,0] op_sel_hi:[0,1,1]
	v_pk_fma_f32 v[56:57], v[114:115], v[20:21], v[56:57] op_sel:[0,0,0] op_sel_hi:[0,1,1]
	v_pk_mul_f32 v[126:127], v[106:107], v[118:119] op_sel:[1,0] op_sel_hi:[1,1]
	v_pk_mul_f32 v[128:129], v[106:107], v[120:121] op_sel:[1,0] op_sel_hi:[1,1]
	v_pk_fma_f32 v[22:23], v[98:99], v[22:23], v[126:127] op_sel:[1,0,0] op_sel_hi:[1,1,1]
	v_pk_fma_f32 v[24:25], v[98:99], v[24:25], v[128:129] op_sel:[1,0,0] op_sel_hi:[1,1,1]
	v_pk_fma_f32 v[54:55], v[114:115], v[22:23], v[54:55] op_sel:[1,0,0] op_sel_hi:[1,1,1]
	v_pk_fma_f32 v[56:57], v[114:115], v[24:25], v[56:57] op_sel:[1,0,0] op_sel_hi:[1,1,1]
	v_pk_mul_f32 v[122:123], v[108:109], v[118:119] op_sel:[0,0] op_sel_hi:[0,1]
	v_pk_mul_f32 v[124:125], v[108:109], v[120:121] op_sel:[0,0] op_sel_hi:[0,1]
	v_pk_fma_f32 v[26:27], v[100:101], v[26:27], v[122:123] op_sel:[0,0,0] op_sel_hi:[0,1,1]
	v_pk_fma_f32 v[28:29], v[100:101], v[28:29], v[124:125] op_sel:[0,0,0] op_sel_hi:[0,1,1]
	v_pk_fma_f32 v[54:55], v[116:117], v[26:27], v[54:55] op_sel:[0,0,0] op_sel_hi:[0,1,1]
	v_pk_fma_f32 v[56:57], v[116:117], v[28:29], v[56:57] op_sel:[0,0,0] op_sel_hi:[0,1,1]
	v_pk_mul_f32 v[126:127], v[108:109], v[118:119] op_sel:[1,0] op_sel_hi:[1,1]
	v_pk_mul_f32 v[128:129], v[108:109], v[120:121] op_sel:[1,0] op_sel_hi:[1,1]
	v_pk_fma_f32 v[30:31], v[100:101], v[30:31], v[126:127] op_sel:[1,0,0] op_sel_hi:[1,1,1]
	v_pk_fma_f32 v[32:33], v[100:101], v[32:33], v[128:129] op_sel:[1,0,0] op_sel_hi:[1,1,1]
	v_pk_fma_f32 v[54:55], v[116:117], v[30:31], v[54:55] op_sel:[1,0,0] op_sel_hi:[1,1,1]
	v_pk_fma_f32 v[56:57], v[116:117], v[32:33], v[56:57] op_sel:[1,0,0] op_sel_hi:[1,1,1]
	ds_write_b128 v136, v[54:57] offset:2560
	ds_read_b128 v[94:97], v134 offset:3584
	ds_read_b128 v[98:101], v134 offset:3600
	ds_read_b128 v[102:105], v134 offset:7680
	ds_read_b128 v[106:109], v134 offset:7696
	ds_read_b128 v[110:113], v134 offset:11776
	ds_read_b128 v[114:117], v134 offset:11792
	ds_read_b128 v[118:121], v135 offset:15872
	s_waitcnt lgkmcnt(7)
; #define LAS __attribute__((address_space(3)))
; __device__ __forceinline__ void hgrn_sample(Frame& F) {
;     ...
; #pragma unroll
;         for (int t = 0; t < 8; ++t) { float op = 0.f;
; #pragma unroll
;             for (int j4 = 0; j4 < 8; ++j4) { const f32x4 f4 = *(const LAS f32x4*)(fs + t * 128 + qd * 32 + 4 * j4), k4 = *(const LAS f32x4*)(ks + t * 128 + qd * 32 + 4 * j4), q4 = *(const LAS f32x4*)(qs + t * 128 + qd * 32 + 4 * j4);
; #pragma unroll
;                 for (int e = 0; e < 4; ++e) { float s = f4[e] * S[4 * j4 + e] + k4[e] * v[t]; S[4 * j4 + e] = s; op += q4[e] * s; } }
;             part[(qd * 8 + t) * 128 + dv] = op; }
	v_pk_mul_f32 v[122:123], v[74:75], v[90:91] op_sel:[0,0] op_sel_hi:[0,1]
	v_pk_mul_f32 v[124:125], v[74:75], v[92:93] op_sel:[0,0] op_sel_hi:[0,1]
	v_pk_fma_f32 v[2:3], v[66:67], v[2:3], v[122:123] op_sel:[0,0,0] op_sel_hi:[0,1,1]
	v_pk_fma_f32 v[4:5], v[66:67], v[4:5], v[124:125] op_sel:[0,0,0] op_sel_hi:[0,1,1]
	v_pk_fma_f32 v[58:59], v[82:83], v[2:3], v[58:59] op_sel:[0,0,0] op_sel_hi:[0,1,1]
	v_pk_fma_f32 v[60:61], v[82:83], v[4:5], v[60:61] op_sel:[0,0,0] op_sel_hi:[0,1,1]
	v_pk_mul_f32 v[126:127], v[74:75], v[90:91] op_sel:[1,0] op_sel_hi:[1,1]
	v_pk_mul_f32 v[128:129], v[74:75], v[92:93] op_sel:[1,0] op_sel_hi:[1,1]
	v_pk_fma_f32 v[6:7], v[66:67], v[6:7], v[126:127] op_sel:[1,0,0] op_sel_hi:[1,1,1]
	v_pk_fma_f32 v[8:9], v[66:67], v[8:9], v[128:129] op_sel:[1,0,0] op_sel_hi:[1,1,1]
	v_pk_fma_f32 v[58:59], v[82:83], v[6:7], v[58:59] op_sel:[1,0,0] op_sel_hi:[1,1,1]
	v_pk_fma_f32 v[60:61], v[82:83], v[8:9], v[60:61] op_sel:[1,0,0] op_sel_hi:[1,1,1]
	v_pk_mul_f32 v[122:123], v[76:77], v[90:91] op_sel:[0,0] op_sel_hi:[0,1]
	v_pk_mul_f32 v[124:125], v[76:77], v[92:93] op_sel:[0,0] op_sel_hi:[0,1]
	v_pk_fma_f32 v[10:11], v[68:69], v[10:11], v[122:123] op_sel:[0,0,0] op_sel_hi:[0,1,1]
	v_pk_fma_f32 v[12:13], v[68:69], v[12:13], v[124:125] op_sel:[0,0,0] op_sel_hi:[0,1,1]
	v_pk_fma_f32 v[58:59], v[84:85], v[10:11], v[58:59] op_sel:[0,0,0] op_sel_hi:[0,1,1]
	v_pk_fma_f32 v[60:61], v[84:85], v[12:13], v[60:61] op_sel:[0,0,0] op_sel_hi:[0,1,1]
	v_pk_mul_f32 v[126:127], v[76:77], v[90:91] op_sel:[1,0] op_sel_hi:[1,1]
	v_pk_mul_f32 v[128:129], v[76:77], v[92:93] op_sel:[1,0] op_sel_hi:[1,1]
	v_pk_fma_f32 v[14:15], v[68:69], v[14:15], v[126:127] op_sel:[1,0,0] op_sel_hi:[1,1,1]
	v_pk_fma_f32 v[16:17], v[68:69], v[16:17], v[128:129] op_sel:[1,0,0] op_sel_hi:[1,1,1]
	v_pk_fma_f32 v[58:59], v[84:85], v[14:15], v[58:59] op_sel:[1,0,0] op_sel_hi:[1,1,1]
	v_pk_fma_f32 v[60:61], v[84:85], v[16:17], v[60:61] op_sel:[1,0,0] op_sel_hi:[1,1,1]
	v_pk_mul_f32 v[122:123], v[78:79], v[90:91] op_sel:[0,0] op_sel_hi:[0,1]
	v_pk_mul_f32 v[124:125], v[78:79], v[92:93] op_sel:[0,0] op_sel_hi:[0,1]
	v_pk_fma_f32 v[18:19], v[70:71], v[18:19], v[122:123] op_sel:[0,0,0] op_sel_hi:[0,1,1]
	v_pk_fma_f32 v[20:21], v[70:71], v[20:21], v[124:125] op_sel:[0,0,0] op_sel_hi:[0,1,1]
	v_pk_fma_f32 v[58:59], v[86:87], v[18:19], v[58:59] op_sel:[0,0,0] op_sel_hi:[0,1,1]
	v_pk_fma_f32 v[60:61], v[86:87], v[20:21], v[60:61] op_sel:[0,0,0] op_sel_hi:[0,1,1]
	v_pk_mul_f32 v[126:127], v[78:79], v[90:91] op_sel:[1,0] op_sel_hi:[1,1]
	v_pk_mul_f32 v[128:129], v[78:79], v[92:93] op_sel:[1,0] op_sel_hi:[1,1]
	v_pk_fma_f32 v[22:23], v[70:71], v[22:23], v[126:127] op_sel:[1,0,0] op_sel_hi:[1,1,1]
	v_pk_fma_f32 v[24:25], v[70:71], v[24:25], v[128:129] op_sel:[1,0,0] op_sel_hi:[1,1,1]
	v_pk_fma_f32 v[58:59], v[86:87], v[22:23], v[58:59] op_sel:[1,0,0] op_sel_hi:[1,1,1]
	v_pk_fma_f32 v[60:61], v[86:87], v[24:25], v[60:61] op_sel:[1,0,0] op_sel_hi:[1,1,1]
	v_pk_mul_f32 v[122:123], v[80:81], v[90:91] op_sel:[0,0] op_sel_hi:[0,1]
	v_pk_mul_f32 v[124:125], v[80:81], v[92:93] op_sel:[0,0] op_sel_hi:[0,1]
	v_pk_fma_f32 v[26:27], v[72:73], v[26:27], v[122:123] op_sel:[0,0,0] op_sel_hi:[0,1,1]
	v_pk_fma_f32 v[28:29], v[72:73], v[28:29], v[124:125] op_sel:[0,0,0] op_sel_hi:[0,1,1]
	v_pk_fma_f32 v[58:59], v[88:89], v[26:27], v[58:59] op_sel:[0,0,0] op_sel_hi:[0,1,1]
	v_pk_fma_f32 v[60:61], v[88:89], v[28:29], v[60:61] op_sel:[0,0,0] op_sel_hi:[0,1,1]
	v_pk_mul_f32 v[126:127], v[80:81], v[90:91] op_sel:[1,0] op_sel_hi:[1,1]
	v_pk_mul_f32 v[128:129], v[80:81], v[92:93] op_sel:[1,0] op_sel_hi:[1,1]
	v_pk_fma_f32 v[30:31], v[72:73], v[30:31], v[126:127] op_sel:[1,0,0] op_sel_hi:[1,1,1]
	v_pk_fma_f32 v[32:33], v[72:73], v[32:33], v[128:129] op_sel:[1,0,0] op_sel_hi:[1,1,1]
	v_pk_fma_f32 v[58:59], v[88:89], v[30:31], v[58:59] op_sel:[1,0,0] op_sel_hi:[1,1,1]
	v_pk_fma_f32 v[60:61], v[88:89], v[32:33], v[60:61] op_sel:[1,0,0] op_sel_hi:[1,1,1]
	ds_write_b128 v136, v[58:61] offset:3072
	s_waitcnt lgkmcnt(0)
	v_pk_mul_f32 v[122:123], v[102:103], v[118:119] op_sel:[0,0] op_sel_hi:[0,1]
	v_pk_mul_f32 v[124:125], v[102:103], v[120:121] op_sel:[0,0] op_sel_hi:[0,1]
	v_pk_fma_f32 v[2:3], v[94:95], v[2:3], v[122:123] op_sel:[0,0,0] op_sel_hi:[0,1,1]
	v_pk_fma_f32 v[4:5], v[94:95], v[4:5], v[124:125] op_sel:[0,0,0] op_sel_hi:[0,1,1]
	v_pk_fma_f32 v[62:63], v[110:111], v[2:3], v[62:63] op_sel:[0,0,0] op_sel_hi:[0,1,1]
	v_pk_fma_f32 v[64:65], v[110:111], v[4:5], v[64:65] op_sel:[0,0,0] op_sel_hi:[0,1,1]
	v_pk_mul_f32 v[126:127], v[102:103], v[118:119] op_sel:[1,0] op_sel_hi:[1,1]
	v_pk_mul_f32 v[128:129], v[102:103], v[120:121] op_sel:[1,0] op_sel_hi:[1,1]
	v_pk_fma_f32 v[6:7], v[94:95], v[6:7], v[126:127] op_sel:[1,0,0] op_sel_hi:[1,1,1]
	v_pk_fma_f32 v[8:9], v[94:95], v[8:9], v[128:129] op_sel:[1,0,0] op_sel_hi:[1,1,1]
	v_pk_fma_f32 v[62:63], v[110:111], v[6:7], v[62:63] op_sel:[1,0,0] op_sel_hi:[1,1,1]
	v_pk_fma_f32 v[64:65], v[110:111], v[8:9], v[64:65] op_sel:[1,0,0] op_sel_hi:[1,1,1]
	v_pk_mul_f32 v[122:123], v[104:105], v[118:119] op_sel:[0,0] op_sel_hi:[0,1]
	v_pk_mul_f32 v[124:125], v[104:105], v[120:121] op_sel:[0,0] op_sel_hi:[0,1]
	v_pk_fma_f32 v[10:11], v[96:97], v[10:11], v[122:123] op_sel:[0,0,0] op_sel_hi:[0,1,1]
	v_pk_fma_f32 v[12:13], v[96:97], v[12:13], v[124:125] op_sel:[0,0,0] op_sel_hi:[0,1,1]
	v_pk_fma_f32 v[62:63], v[112:113], v[10:11], v[62:63] op_sel:[0,0,0] op_sel_hi:[0,1,1]
	v_pk_fma_f32 v[64:65], v[112:113], v[12:13], v[64:65] op_sel:[0,0,0] op_sel_hi:[0,1,1]
	v_pk_mul_f32 v[126:127], v[104:105], v[118:119] op_sel:[1,0] op_sel_hi:[1,1]
	v_pk_mul_f32 v[128:129], v[104:105], v[120:121] op_sel:[1,0] op_sel_hi:[1,1]
; __device__ __forceinline__ unsigned f2bf(float f) { return pk2(f, 0.f) & 0xffffu; }
; __device__ __forceinline__ void hgrn_sample(Frame& F) {
;     ...
;                 for (int e = 0; e < 4; ++e) { float s = f4[e] * S[4 * j4 + e] + k4[e] * v[t]; S[4 * j4 + e] = s; op += q4[e] * s; } }
;             part[(qd * 8 + t) * 128 + dv] = op; }
;         float* so = F.o_hgrn_s + ((size_t)b * 4 + h) * 128 * 128;
; #pragma unroll
;         for (int j = 0; j < 32; ++j) so[(size_t)(qd * 32 + j) * 128 + dv] = S[j];
;         __syncthreads();
;         float o2[2];
; #pragma unroll
;         for (int i = 0; i < 2; ++i) { const int idx = tid + 512 * i, t = idx >> 7, d2 = idx & 127;
;             const float o = (part[(0 * 8 + t) * 128 + d2] + part[(1 * 8 + t) * 128 + d2]) + (part[(2 * 8 + t) * 128 + d2] + part[(3 * 8 + t) * 128 + d2]);
;             o2[i] = o; const float ssq = wave_sum(o * o); if (F.lane == 0) red[i * 8 + F.wave] = ssq; }
;         __syncthreads();
; #pragma unroll
;         for (int i = 0; i < 2; ++i) { const int idx = tid + 512 * i, t = idx >> 7, d2 = idx & 127; const float tot = red[i * 8 + (F.wave & ~1)] + red[i * 8 + (F.wave | 1)];
;             const size_t r = (size_t)(row0 + t);
;             F.MIX[r * D + 256 + h * 128 + d2] = (bf16)f2bf(o2[i] * (__builtin_amdgcn_rsqf(tot * (1.f / 128.f) + EPS)) * ogv * bf2f(gsv[i])); }
	v_pk_fma_f32 v[14:15], v[96:97], v[14:15], v[126:127] op_sel:[1,0,0] op_sel_hi:[1,1,1]
	v_pk_fma_f32 v[16:17], v[96:97], v[16:17], v[128:129] op_sel:[1,0,0] op_sel_hi:[1,1,1]
	v_pk_fma_f32 v[62:63], v[112:113], v[14:15], v[62:63] op_sel:[1,0,0] op_sel_hi:[1,1,1]
	v_pk_fma_f32 v[64:65], v[112:113], v[16:17], v[64:65] op_sel:[1,0,0] op_sel_hi:[1,1,1]
	v_pk_mul_f32 v[122:123], v[106:107], v[118:119] op_sel:[0,0] op_sel_hi:[0,1]
	v_pk_mul_f32 v[124:125], v[106:107], v[120:121] op_sel:[0,0] op_sel_hi:[0,1]
	v_pk_fma_f32 v[18:19], v[98:99], v[18:19], v[122:123] op_sel:[0,0,0] op_sel_hi:[0,1,1]
	v_pk_fma_f32 v[20:21], v[98:99], v[20:21], v[124:125] op_sel:[0,0,0] op_sel_hi:[0,1,1]
	v_pk_fma_f32 v[62:63], v[114:115], v[18:19], v[62:63] op_sel:[0,0,0] op_sel_hi:[0,1,1]
	v_pk_fma_f32 v[64:65], v[114:115], v[20:21], v[64:65] op_sel:[0,0,0] op_sel_hi:[0,1,1]
	v_pk_mul_f32 v[126:127], v[106:107], v[118:119] op_sel:[1,0] op_sel_hi:[1,1]
	v_pk_mul_f32 v[128:129], v[106:107], v[120:121] op_sel:[1,0] op_sel_hi:[1,1]
	v_pk_fma_f32 v[22:23], v[98:99], v[22:23], v[126:127] op_sel:[1,0,0] op_sel_hi:[1,1,1]
	v_pk_fma_f32 v[24:25], v[98:99], v[24:25], v[128:129] op_sel:[1,0,0] op_sel_hi:[1,1,1]
	v_pk_fma_f32 v[62:63], v[114:115], v[22:23], v[62:63] op_sel:[1,0,0] op_sel_hi:[1,1,1]
	v_pk_fma_f32 v[64:65], v[114:115], v[24:25], v[64:65] op_sel:[1,0,0] op_sel_hi:[1,1,1]
	v_pk_mul_f32 v[122:123], v[108:109], v[118:119] op_sel:[0,0] op_sel_hi:[0,1]
	v_pk_mul_f32 v[124:125], v[108:109], v[120:121] op_sel:[0,0] op_sel_hi:[0,1]
	v_pk_fma_f32 v[26:27], v[100:101], v[26:27], v[122:123] op_sel:[0,0,0] op_sel_hi:[0,1,1]
	v_pk_fma_f32 v[28:29], v[100:101], v[28:29], v[124:125] op_sel:[0,0,0] op_sel_hi:[0,1,1]
	v_pk_fma_f32 v[62:63], v[116:117], v[26:27], v[62:63] op_sel:[0,0,0] op_sel_hi:[0,1,1]
	v_pk_fma_f32 v[64:65], v[116:117], v[28:29], v[64:65] op_sel:[0,0,0] op_sel_hi:[0,1,1]
	v_pk_mul_f32 v[126:127], v[108:109], v[118:119] op_sel:[1,0] op_sel_hi:[1,1]
	v_pk_mul_f32 v[128:129], v[108:109], v[120:121] op_sel:[1,0] op_sel_hi:[1,1]
	v_pk_fma_f32 v[30:31], v[100:101], v[30:31], v[126:127] op_sel:[1,0,0] op_sel_hi:[1,1,1]
	v_pk_fma_f32 v[32:33], v[100:101], v[32:33], v[128:129] op_sel:[1,0,0] op_sel_hi:[1,1,1]
	v_pk_fma_f32 v[62:63], v[116:117], v[30:31], v[62:63] op_sel:[1,0,0] op_sel_hi:[1,1,1]
	v_pk_fma_f32 v[64:65], v[116:117], v[32:33], v[64:65] op_sel:[1,0,0] op_sel_hi:[1,1,1]
	ds_write_b128 v136, v[62:65] offset:3584
	global_store_dwordx4 v132, v[2:5], s[62:63]
	global_store_dwordx4 v132, v[6:9], s[62:63] offset:512
	global_store_dwordx4 v132, v[10:13], s[62:63] offset:1024
	global_store_dwordx4 v132, v[14:17], s[62:63] offset:1536
	global_store_dwordx4 v132, v[18:21], s[62:63] offset:2048
	global_store_dwordx4 v132, v[22:25], s[62:63] offset:2560
	global_store_dwordx4 v132, v[26:29], s[62:63] offset:3072
	global_store_dwordx4 v132, v[30:33], s[62:63] offset:3584
	s_waitcnt lgkmcnt(0)
	s_barrier
	ds_read_b64 v[66:67], v141 offset:0
	ds_read_b64 v[68:69], v141 offset:4096
	ds_read_b64 v[70:71], v141 offset:8192
	ds_read_b64 v[72:73], v141 offset:12288
	ds_read_b64 v[74:75], v141 offset:16384
	ds_read_b64 v[76:77], v141 offset:20480
	ds_read_b64 v[78:79], v141 offset:24576
	ds_read_b64 v[80:81], v141 offset:28672
	ds_read_b64 v[82:83], v141 offset:32768
	ds_read_b64 v[84:85], v141 offset:36864
	ds_read_b64 v[86:87], v141 offset:40960
	ds_read_b64 v[88:89], v141 offset:45056
	ds_read_b64 v[90:91], v141 offset:49152
	ds_read_b64 v[92:93], v141 offset:53248
	ds_read_b64 v[94:95], v141 offset:57344
	ds_read_b64 v[96:97], v141 offset:61440
	s_waitcnt lgkmcnt(0)
	v_pk_add_f32 v[66:67], v[66:67], v[82:83]
	v_pk_add_f32 v[68:69], v[68:69], v[84:85]
	v_pk_add_f32 v[70:71], v[70:71], v[86:87]
	v_pk_add_f32 v[72:73], v[72:73], v[88:89]
	v_pk_add_f32 v[74:75], v[74:75], v[90:91]
	v_pk_add_f32 v[76:77], v[76:77], v[92:93]
	v_pk_add_f32 v[78:79], v[78:79], v[94:95]
	v_pk_add_f32 v[80:81], v[80:81], v[96:97]
	v_pk_add_f32 v[66:67], v[66:67], v[74:75]
	v_pk_add_f32 v[68:69], v[68:69], v[76:77]
	v_pk_add_f32 v[70:71], v[70:71], v[78:79]
	v_pk_add_f32 v[72:73], v[72:73], v[80:81]
	v_pk_add_f32 v[66:67], v[66:67], v[70:71]
	v_pk_add_f32 v[68:69], v[68:69], v[72:73]
	v_pk_add_f32 v[66:67], v[66:67], v[68:69]
	v_mul_f32_e32 v148, v66, v66
	v_fmac_f32_e32 v148, v67, v67
	s_nop 1
	v_add_f32_dpp v148, v148, v148 row_ror:8 row_mask:0xf bank_mask:0xf
	s_nop 1
	v_add_f32_dpp v148, v148, v148 row_ror:4 row_mask:0xf bank_mask:0xf
	s_nop 1
	v_add_f32_dpp v148, v148, v148 row_ror:2 row_mask:0xf bank_mask:0xf
	s_nop 1
	v_add_f32_dpp v148, v148, v148 row_ror:1 row_mask:0xf bank_mask:0xf
	s_nop 1
	v_readlane_b32 s74, v148, 0
	v_readlane_b32 s75, v148, 16
	v_readlane_b32 s76, v148, 32
	v_readlane_b32 s77, v148, 48
	s_nop 3
	v_mov_b32_e32 v148, s74
	v_add_f32_e32 v148, s75, v148
	v_mov_b32_e32 v150, s76
	v_add_f32_e32 v150, s77, v150
	v_add_f32_e32 v148, v148, v150
	v_mov_b32_e32 v150, 0x358637bd
	v_fmamk_f32 v148, v148, 0x3c000000, v150
	v_rsq_f32_e32 v148, v148
	v_lshlrev_b32_e32 v150, 16, v140
	v_and_b32_e32 v140, 0xffff0000, v140
	v_mul_f32_e32 v66, v66, v148
	v_mul_f32_e32 v67, v67, v148
	v_mul_f32_e32 v66, v66, v138
	v_mul_f32_e32 v67, v67, v139
	v_mul_f32_e32 v66, v66, v150
	v_mul_f32_e32 v67, v67, v140
	v_cvt_pk_bf16_f32 v66, v66, v67
	s_add_i32 s74, s58, s43
	s_lshl_b32 s74, s74, 11
	s_lshl_b32 s75, s57, 8
	s_add_i32 s74, s74, s75
	s_add_i32 s74, s74, 0x200
	s_add_u32 s76, s48, 0x5300000
	s_addc_u32 s77, s49, 0
	s_add_u32 s76, s76, s74
	s_addc_u32 s77, s77, 0
	global_store_dword v142, v66, s[76:77]
	s_add_i32 s55, s55, s79
	s_branch .Lhs_loop_a
.Lhs_done_a:
	s_barrier
	v_xor_b32_e32 v22, 16, v202
	v_xor_b32_e32 v23, 32, v202
	v_lshlrev_b32_e32 v22, 2, v22
	v_lshlrev_b32_e32 v23, 2, v23

; __device__ __forceinline__ void hgrn_sample(Frame& F) {
;     ...
;     const int tid = F.tid, dv = tid & 127, qd = tid >> 7;
;     for (int u = blockIdx.x; u < 512; u += F.G) {
;         const int b = u >> 2, h = u & 3, row0 = TP + b * 8;
;         float S[32];
; #pragma unroll
;         for (int j = 0; j < 32; ++j) S[j] = F.state_hgrn[(((size_t)b * 4 + h) * 128 + qd * 32 + j) * 128 + dv];
; #pragma unroll
;         for (int i = 0; i < 2; ++i) { const int idx = tid + 512 * i, t = idx >> 7, cc = idx & 127; const size_t ro = (size_t)(row0 + t) * 512 + h * 128 + cc;
;             qs[idx] = bf2f(F.Q[ro]); fs[idx] = __expf((float)F.LOGF[ro]); ks[idx] = 1.f - fs[idx]; }
;         float v[8];
; #pragma unroll
;         for (int t = 0; t < 8; ++t) v[t] = bf2f(F.V[(size_t)(row0 + t) * 512 + h * 128 + dv]);
;         const float ogv = F.onorm_g[h * 128 + dv]; bf16 gsv[2];
; #pragma unroll
;         for (int i = 0; i < 2; ++i) gsv[i] = F.GS[(size_t)(row0 + ((tid + 512 * i) >> 7)) * 512 + h * 128 + dv];
.LBB0_690:
	s_andn2_b64 vcc, exec, s[92:93]
	s_cbranch_vccnz .LBB0_704
	s_cmpk_gt_i32 s88, 0x1ff
	s_cbranch_scc1 .LBB0_704
	v_readfirstlane_b32 s43, v0
	v_readlane_b32 s44, v254, 11
	v_readlane_b32 s45, v254, 12
	v_readlane_b32 s46, v254, 33
	v_readlane_b32 s47, v254, 34
	v_readlane_b32 s48, v254, 19
	v_readlane_b32 s49, v254, 20
	v_readlane_b32 s50, v254, 58
	v_readlane_b32 s51, v254, 59
	v_and_b32_e32 v130, 15, v202
	v_lshrrev_b32_e32 v131, 4, v202
	s_lshr_b32 s43, s43, 6
	s_sub_u32 s48, s48, 0x4000
	s_subb_u32 s49, s49, 0
	s_add_u32 s50, s50, 0x4c2a000
	s_addc_u32 s51, s51, 0
	s_lshl_b32 s54, s43, 2
	v_add_u32_e32 v137, s54, v131
	v_and_b32_e32 v148, 1, v137
	v_lshrrev_b32_e32 v150, 1, v137
	v_lshlrev_b32_e32 v135, 4, v130
	v_lshl_add_u32 v135, v148, 8, v135
	v_lshl_add_u32 v132, v150, 12, v135
	v_lshlrev_b32_e32 v134, 5, v150
	v_add_u32_e32 v136, 0x8000, v132
	v_lshlrev_b32_e32 v133, 2, v0
	s_lshl_b32 s54, s43, 9
	s_add_i32 s54, s54, 0x8000
	v_lshl_add_u32 v141, v202, 3, s54
	s_mov_b32 s55, s88
